# baseline (speedup 1.0000x reference)
; #define LAS __attribute__((address_space(3)))
; __device__ __forceinline__ unsigned xb_xcc_id() { return (unsigned)__builtin_amdgcn_s_getreg((3 << 11) | 20) & 0xFu; }
; __global__ void __launch_bounds__(512) mk_fwd(Params p) {
;     ...
;         if (ph + 1 < p.ph_hi) {
;             XcdBarrier xbar; xbar.bar = (unsigned*)(cx.ws + WS_BAR); xbar.x = xb_xcc_id(); xbar.st = (volatile LAS unsigned*)(lds + LDS_MISC);
;             if (p.ph_hi < 0) grid.sync();
.LBB0_551:
	v_readlane_b32 s44, v255, 4
	s_add_i32 s44, s44, 1
	v_readlane_b32 s0, v254, 9
	s_cmp_ge_i32 s44, s0
	s_mov_b64 s[2:3], -1
	v_readlane_b32 s45, v254, 39
	s_cbranch_scc1 .LBB0_31
	v_readlane_b32 s2, v254, 37
	v_readlane_b32 s3, v254, 38
	s_andn2_b64 vcc, exec, s[2:3]
	s_getreg_b32 s0, hwreg(HW_REG_XCC_ID, 0, 4)
	s_cbranch_vccnz .LBB0_564
	s_waitcnt lgkmcnt(0)
	s_barrier
	s_mov_b64 s[2:3], exec
	v_readlane_b32 s4, v255, 0
	v_readlane_b32 s5, v255, 1
	s_and_b64 s[4:5], s[2:3], s[4:5]
	s_mov_b64 exec, s[4:5]
	s_cbranch_execz .LBB0_563
	v_readlane_b32 s4, v254, 3
	v_readlane_b32 s5, v254, 4
	s_nop 3
	s_load_dwordx2 s[4:5], s[4:5], 0x58
	buffer_wbl2 sc1
	s_mov_b64 s[6:7], exec
	v_mbcnt_lo_u32_b32 v1, s6, 0
	v_mbcnt_hi_u32_b32 v1, s7, v1
	v_cmp_eq_u32_e32 vcc, 0, v1
	s_waitcnt lgkmcnt(0)
	global_load_dword v0, v181, s[4:5] offset:40
	s_waitcnt vmcnt(0)
	s_and_saveexec_b64 s[8:9], vcc
	s_cbranch_execz .LBB0_556
	s_bcnt1_i32_b64 s6, s[6:7]
	v_mov_b32_e32 v2, s6
	global_atomic_add v2, v181, v2, s[4:5] offset:32 sc0
